# adds: group A reads the first V-fragment batch of P.V(t) at the tail of its softmax (in front of the bf16 packing) into spare VGPRs
# baseline (speedup 1.0000x reference)
.LBB0_154:
	v_cndmask_b32_e64 v232, v235, v232, s[42:43]
	v_mul_f32_e32 v210, 0xbfb8aa3b, v232
	v_fmamk_f32 v80, v80, 0x3fb8aa3b, v210
	v_fmamk_f32 v81, v81, 0x3fb8aa3b, v210
	v_fmamk_f32 v82, v82, 0x3fb8aa3b, v210
	v_fmamk_f32 v83, v83, 0x3fb8aa3b, v210
	v_fmamk_f32 v84, v84, 0x3fb8aa3b, v210
	v_fmamk_f32 v85, v85, 0x3fb8aa3b, v210
	v_fmamk_f32 v86, v86, 0x3fb8aa3b, v210
	v_fmamk_f32 v87, v87, 0x3fb8aa3b, v210
	v_fmamk_f32 v88, v88, 0x3fb8aa3b, v210
	v_fmamk_f32 v89, v89, 0x3fb8aa3b, v210
	v_fmamk_f32 v90, v90, 0x3fb8aa3b, v210
	v_fmamk_f32 v91, v91, 0x3fb8aa3b, v210
	v_fmamk_f32 v92, v92, 0x3fb8aa3b, v210
	v_fmamk_f32 v93, v93, 0x3fb8aa3b, v210
	v_fmamk_f32 v94, v94, 0x3fb8aa3b, v210
	v_fmamk_f32 v95, v95, 0x3fb8aa3b, v210
	v_fmamk_f32 v64, v64, 0x3fb8aa3b, v210
	v_fmamk_f32 v65, v65, 0x3fb8aa3b, v210
	v_fmamk_f32 v66, v66, 0x3fb8aa3b, v210
	v_fmamk_f32 v67, v67, 0x3fb8aa3b, v210
	v_fmamk_f32 v68, v68, 0x3fb8aa3b, v210
	v_fmamk_f32 v69, v69, 0x3fb8aa3b, v210
	v_fmamk_f32 v70, v70, 0x3fb8aa3b, v210
	v_fmamk_f32 v71, v71, 0x3fb8aa3b, v210
	v_fmamk_f32 v72, v72, 0x3fb8aa3b, v210
	v_fmamk_f32 v73, v73, 0x3fb8aa3b, v210
	v_fmamk_f32 v74, v74, 0x3fb8aa3b, v210
	v_fmamk_f32 v75, v75, 0x3fb8aa3b, v210
	v_fmamk_f32 v76, v76, 0x3fb8aa3b, v210
	v_fmamk_f32 v77, v77, 0x3fb8aa3b, v210
	v_fmamk_f32 v78, v78, 0x3fb8aa3b, v210
	v_fmac_f32_e32 v210, 0x3fb8aa3b, v79
	v_exp_f32_e32 v79, v80
	v_exp_f32_e32 v211, v81
	v_exp_f32_e32 v82, v82
	v_exp_f32_e32 v83, v83
	v_exp_f32_e32 v84, v84
	v_exp_f32_e32 v212, v68
	v_add_f32_e32 v68, 0, v79
	v_exp_f32_e32 v85, v85
	v_add_f32_e32 v68, v211, v68
	v_exp_f32_e32 v86, v86
	v_add_f32_e32 v68, v82, v68
	v_exp_f32_e32 v87, v87
	v_add_f32_e32 v68, v83, v68
	v_exp_f32_e32 v88, v88
	v_add_f32_e32 v68, v84, v68
	v_exp_f32_e32 v89, v89
	v_add_f32_e32 v68, v85, v68
	v_exp_f32_e32 v90, v90
	v_add_f32_e32 v68, v86, v68
	v_exp_f32_e32 v91, v91
	v_add_f32_e32 v68, v87, v68
	v_exp_f32_e32 v92, v92
	v_add_f32_e32 v68, v88, v68
	v_exp_f32_e32 v93, v93
	v_add_f32_e32 v68, v89, v68
	v_exp_f32_e32 v94, v94
	v_add_f32_e32 v68, v90, v68
	v_exp_f32_e32 v95, v95
	v_add_f32_e32 v68, v91, v68
	v_exp_f32_e32 v64, v64
	v_add_f32_e32 v68, v92, v68
	v_exp_f32_e32 v65, v65
	v_add_f32_e32 v68, v93, v68
	v_exp_f32_e32 v66, v66
	v_add_f32_e32 v68, v94, v68
	v_exp_f32_e32 v67, v67
	v_add_f32_e32 v68, v95, v68
	v_add_f32_e32 v68, v64, v68
	v_exp_f32_e32 v213, v69
	v_add_f32_e32 v68, v65, v68
	v_exp_f32_e32 v235, v70
	v_add_f32_e32 v68, v66, v68
	v_exp_f32_e32 v71, v71
	v_add_f32_e32 v68, v67, v68
	v_exp_f32_e32 v240, v72
	v_add_f32_e32 v68, v212, v68
	v_exp_f32_e32 v241, v73
	v_add_f32_e32 v68, v213, v68
	v_exp_f32_e32 v242, v74
	v_add_f32_e32 v68, v235, v68
	v_exp_f32_e32 v243, v75
	v_add_f32_e32 v68, v71, v68
	v_exp_f32_e32 v244, v76
	v_add_f32_e32 v68, v240, v68
	v_exp_f32_e32 v245, v77
	v_add_f32_e32 v68, v241, v68
	v_exp_f32_e32 v246, v78
	v_add_f32_e32 v68, v242, v68
	v_exp_f32_e32 v210, v210
	v_add_f32_e32 v68, v243, v68
	v_add_f32_e32 v68, v244, v68
	v_add_f32_e32 v68, v245, v68
	v_add_f32_e32 v68, v246, v68
	v_add_f32_e32 v80, v210, v68
	v_mov_b32_e32 v81, v80
	s_and_b64 vcc, exec, s[80:81]
	s_cbranch_vccnz .Lpv5_askip
	v_lshl_add_u32 v216, s70, 14, v218
	ds_read_b64_tr_b16 v[154:155], v216 offset:0x0
	ds_read_b64_tr_b16 v[156:157], v216 offset:0x800
	ds_read_b64_tr_b16 v[158:159], v216 offset:0x1000
	ds_read_b64_tr_b16 v[160:161], v216 offset:0x1800
	ds_read_b64_tr_b16 v[162:163], v216 offset:0x2000
	ds_read_b64_tr_b16 v[164:165], v216 offset:0x2800
	ds_read_b64_tr_b16 v[206:207], v216 offset:0x3000
	ds_read_b64_tr_b16 v[208:209], v216 offset:0x3800
.Lpv5_askip:
	v_cvt_pk_bf16_f32 v76, v79, v211
	v_cvt_pk_bf16_f32 v77, v82, v83
	v_cvt_pk_bf16_f32 v78, v84, v85
	v_cvt_pk_bf16_f32 v79, v86, v87
	v_cvt_pk_bf16_f32 v72, v88, v89
	v_cvt_pk_bf16_f32 v73, v90, v91
	v_cvt_pk_bf16_f32 v74, v92, v93
	v_cvt_pk_bf16_f32 v75, v94, v95
	v_cvt_pk_bf16_f32 v68, v64, v65
	v_cvt_pk_bf16_f32 v69, v66, v67
	v_cvt_pk_bf16_f32 v70, v212, v213
	v_cvt_pk_bf16_f32 v71, v235, v71
	v_cvt_pk_bf16_f32 v64, v240, v241
	v_cvt_pk_bf16_f32 v65, v242, v243
	v_cvt_pk_bf16_f32 v66, v244, v245
	v_cvt_pk_bf16_f32 v67, v246, v210
	s_nop 1
	v_permlane32_swap_b32_e32 v80, v81
	v_permlane32_swap_b32_e32 v76, v78
	v_permlane32_swap_b32_e32 v77, v79
	v_permlane32_swap_b32_e32 v72, v74
	v_permlane32_swap_b32_e32 v73, v75
	v_permlane32_swap_b32_e32 v68, v70
	v_permlane32_swap_b32_e32 v69, v71
	v_permlane32_swap_b32_e32 v64, v66
	v_permlane32_swap_b32_e32 v65, v67
	s_andn2_b64 vcc, exec, s[76:77]
	s_cbranch_vccnz .LBB0_156
	v_lshl_add_u32 v94, s70, 14, v218
	s_waitcnt lgkmcnt(0)
	s_nop 0
	v_mfma_f32_32x32x16_bf16 v[32:47], v[76:79], v[154:157], v[32:47]
	ds_read_b64_tr_b16 v[82:83], v94 offset:0x200
	ds_read_b64_tr_b16 v[84:85], v94 offset:0xa00
	v_mfma_f32_32x32x16_bf16 v[32:47], v[72:75], v[158:161], v[32:47]
	ds_read_b64_tr_b16 v[86:87], v94 offset:0x1200
	ds_read_b64_tr_b16 v[88:89], v94 offset:0x1a00
	v_mfma_f32_32x32x16_bf16 v[32:47], v[68:71], v[162:165], v[32:47]
	ds_read_b64_tr_b16 v[90:91], v94 offset:0x2200
	ds_read_b64_tr_b16 v[92:93], v94 offset:0x2a00
	v_mfma_f32_32x32x16_bf16 v[32:47], v[64:67], v[206:209], v[32:47]
	ds_read_b64_tr_b16 v[210:211], v94 offset:0x3200
	ds_read_b64_tr_b16 v[212:213], v94 offset:0x3a00
	s_waitcnt lgkmcnt(0)
	v_mfma_f32_32x32x16_bf16 v[48:63], v[76:79], v[82:85], v[48:63]
	ds_read_b64_tr_b16 v[82:83], v94 offset:0x400
	ds_read_b64_tr_b16 v[84:85], v94 offset:0xc00
	v_mfma_f32_32x32x16_bf16 v[48:63], v[72:75], v[86:89], v[48:63]
	ds_read_b64_tr_b16 v[86:87], v94 offset:0x1400
	ds_read_b64_tr_b16 v[88:89], v94 offset:0x1c00
	v_mfma_f32_32x32x16_bf16 v[48:63], v[68:71], v[90:93], v[48:63]
	ds_read_b64_tr_b16 v[90:91], v94 offset:0x2400
	ds_read_b64_tr_b16 v[92:93], v94 offset:0x2c00
	v_mfma_f32_32x32x16_bf16 v[48:63], v[64:67], v[210:213], v[48:63]
	ds_read_b64_tr_b16 v[210:211], v94 offset:0x3400
	ds_read_b64_tr_b16 v[212:213], v94 offset:0x3c00
	s_waitcnt lgkmcnt(0)
	v_mfma_f32_32x32x16_bf16 v[16:31], v[76:79], v[82:85], v[16:31]
	ds_read_b64_tr_b16 v[82:83], v94 offset:0x600
	ds_read_b64_tr_b16 v[84:85], v94 offset:0xe00
	v_mfma_f32_32x32x16_bf16 v[16:31], v[72:75], v[86:89], v[16:31]
	ds_read_b64_tr_b16 v[86:87], v94 offset:0x1600
	ds_read_b64_tr_b16 v[88:89], v94 offset:0x1e00
	v_mfma_f32_32x32x16_bf16 v[16:31], v[68:71], v[90:93], v[16:31]
	ds_read_b64_tr_b16 v[90:91], v94 offset:0x2600
	ds_read_b64_tr_b16 v[92:93], v94 offset:0x2e00
	v_mfma_f32_32x32x16_bf16 v[16:31], v[64:67], v[210:213], v[16:31]
	ds_read_b64_tr_b16 v[210:211], v94 offset:0x3600
	ds_read_b64_tr_b16 v[212:213], v94 offset:0x3e00
	s_waitcnt lgkmcnt(0)
	v_mfma_f32_32x32x16_bf16 v[0:15], v[76:79], v[82:85], v[0:15]
	v_mfma_f32_32x32x16_bf16 v[0:15], v[72:75], v[86:89], v[0:15]
	v_mfma_f32_32x32x16_bf16 v[0:15], v[68:71], v[90:93], v[0:15]
	v_mfma_f32_32x32x16_bf16 v[0:15], v[64:67], v[210:213], v[0:15]
